# in-proj l1 epilogue: bj=1 shift/scale vectors preloaded with bj=0 loads (free frag VGPRs), k=8 vmcnt(0) round trip removed
# speedup vs baseline: 1.0033x; 1.0033x over previous
;     __device__ __forceinline__ void operator()(const f32x4 (&acc)[2][2][4][2], const Unit& u, int wr, int wc, int fr, int fq) const {
;     ...
;             const int c0 = u.pn * 256 + bj * 128 + wc * 32 + 8 * fq;
;             if (c0 >= INC) continue;
; #pragma unroll
;             for (int ai = 0; ai < 2; ++ai)
; #pragma unroll
;                 for (int m = 0; m < 4; ++m) {
;                     const int r = EPI_ROW(u, ai, wr, m, fr);
;                     f32x4 v0 = acc[ai][bj][m][0], v1 = acc[ai][bj][m][1];
;                     if (rs) {
;                         const float rstd = rsqrtf(rs[r] * (1.f / 1024.f) + EPS);
;                         const float* sp = shw + (size_t)batch_of(r) * INPAD + c0;
;                         v0 = v0 * rstd + *(const f32x4*)sp; v1 = v1 * rstd + *(const f32x4*)(sp + 4);
.LBB0_238:
	s_lshl_b32 s24, s10, 8
	v_or_b32_e32 v4, s24, v153
	s_movk_i32 s2, 0x720
	v_cmp_gt_i32_e32 vcc, s2, v4
	v_ashrrev_i32_e32 v7, 31, v4
	s_and_saveexec_b64 s[54:55], vcc
	s_cbranch_execz .LBB0_342
	s_lshl_b32 s25, s69, 8
	s_add_i32 s70, s25, s4
	v_or_b32_e32 v146, s70, v141
	v_cndmask_b32_e64 v148, 0, 1, s[72:73]
	v_mov_b32_e32 v6, v4
	v_ashrrev_i32_e32 v147, 31, v146
	v_cmp_ne_u32_e64 s[40:41], 1, v148
	s_andn2_b64 vcc, exec, s[72:73]
	v_cmp_gt_i32_e64 s[42:43], s89, v146
	s_cbranch_vccnz .LBB0_241
	v_readlane_b32 s2, v251, 45
	v_readlane_b32 s3, v251, 46
	s_nop 1
	v_lshl_add_u64 v[148:149], v[146:147], 2, s[2:3]
	global_load_dword v162, v[148:149], off
	global_load_dword v232, v[148:149], off
	global_load_dword v233, v[148:149], off offset:64
	global_load_dword v234, v[148:149], off offset:128
	global_load_dword v235, v[148:149], off offset:192
	global_load_dword v236, v[148:149], off offset:512
	global_load_dword v237, v[148:149], off offset:576
	global_load_dword v238, v[148:149], off offset:640
	global_load_dword v239, v[148:149], off offset:704
	s_add_i32 s3, s70, 0xffff0000
	s_lshr_b32 s3, s3, 6
	s_ashr_i32 s2, s70, 12
	s_add_i32 s3, s3, 16
	v_mov_b32_e32 v148, s3
	v_mov_b32_e32 v149, s2
	v_cndmask_b32_e64 v148, v148, v149, s[42:43]
	v_ashrrev_i32_e32 v149, 31, v148
	v_lshlrev_b64 v[148:149], 13, v[148:149]
	v_lshl_add_u64 v[148:149], s[56:57], 0, v[148:149]
	v_lshl_add_u64 v[158:159], v[6:7], 2, v[148:149]
	global_load_dwordx4 v[148:151], v[158:159], off
	global_load_dwordx4 v[164:167], v[158:159], off offset:512
	global_load_dwordx4 v[168:171], v[158:159], off offset:528
	global_load_dwordx4 v[158:161], v[158:159], off offset:16
	s_waitcnt vmcnt(0)
	v_mov_b32_e32 v240, v148
	v_mov_b32_e32 v241, v149
	v_mov_b32_e32 v242, v150
	v_mov_b32_e32 v243, v151
	v_mov_b32_e32 v244, v158
	v_mov_b32_e32 v245, v159
	v_mov_b32_e32 v246, v160
	v_mov_b32_e32 v247, v161
	v_fmamk_f32 v162, v162, 0x3a800000, v214
	v_mul_f32_e32 v163, 0x4b800000, v162
	v_cmp_gt_f32_e32 vcc, s9, v162
	s_nop 1
	v_cndmask_b32_e32 v162, v162, v163, vcc
	v_rsq_f32_e32 v162, v162
	s_nop 0
	v_mul_f32_e32 v163, 0x45800000, v162
	v_cndmask_b32_e32 v162, v162, v163, vcc
	v_pk_fma_f32 v[130:131], v[130:131], v[162:163], v[150:151] op_sel_hi:[1,0,1]
	v_pk_fma_f32 v[128:129], v[128:129], v[162:163], v[148:149] op_sel_hi:[1,0,1]
	v_pk_fma_f32 v[126:127], v[126:127], v[162:163], v[160:161] op_sel_hi:[1,0,1]
	v_pk_fma_f32 v[124:125], v[124:125], v[162:163], v[158:159] op_sel_hi:[1,0,1]

;     __device__ __forceinline__ void operator()(const f32x4 (&acc)[2][2][4][2], const Unit& u, int wr, int wc, int fr, int fq) const {
;     ...
;             const int c0 = u.pn * 256 + bj * 128 + wc * 32 + 8 * fq;
;             if (c0 >= INC) continue;
; #pragma unroll
;             for (int ai = 0; ai < 2; ++ai)
; #pragma unroll
;                 for (int m = 0; m < 4; ++m) {
;                     const int r = EPI_ROW(u, ai, wr, m, fr);
;                     f32x4 v0 = acc[ai][bj][m][0], v1 = acc[ai][bj][m][1];
;                     if (rs) {
;                         const float rstd = rsqrtf(rs[r] * (1.f / 1024.f) + EPS);
;                         const float* sp = shw + (size_t)batch_of(r) * INPAD + c0;
;                         v0 = v0 * rstd + *(const f32x4*)sp; v1 = v1 * rstd + *(const f32x4*)(sp + 4);
.LBB0_342:
	s_or_b64 exec, exec, s[54:55]
	v_or_b32_e32 v6, 0x80, v4
	s_movk_i32 s2, 0x720
	v_cmp_gt_i32_e32 vcc, s2, v6
	s_and_saveexec_b64 s[54:55], vcc
	s_cbranch_execz .LBB0_445
	s_lshl_b32 s25, s69, 8
	s_add_i32 s69, s25, s4
	v_or_b32_e32 v76, s69, v141
	v_ashrrev_i32_e32 v77, 31, v76
	s_mov_b64 s[2:3], -1
	s_and_b64 vcc, exec, s[72:73]
	v_cmp_gt_i32_e64 s[40:41], s89, v76
	s_cbranch_vccz .LBB0_345
	v_readlane_b32 s2, v251, 45
	v_readlane_b32 s3, v251, 46
	s_nop 1
	v_lshl_add_u64 v[68:69], v[76:77], 2, s[2:3]
	v_mov_b32_e32 v78, v232
	s_add_i32 s3, s69, 0xffff0000
	s_lshr_b32 s3, s3, 6
	s_ashr_i32 s2, s69, 12
	s_add_i32 s3, s3, 16
	v_mov_b32_e32 v6, s3
	v_mov_b32_e32 v68, s2
	v_cndmask_b32_e64 v68, v6, v68, s[40:41]
	v_ashrrev_i32_e32 v69, 31, v68
	v_lshlrev_b64 v[68:69], 13, v[68:69]
	v_lshl_add_u64 v[68:69], s[56:57], 0, v[68:69]
	v_mov_b32_e32 v6, v4
	v_lshl_add_u64 v[72:73], v[6:7], 2, v[68:69]
	s_nop 0
	s_mov_b64 s[2:3], 0
	v_mov_b32_e32 v68, v164
	v_mov_b32_e32 v69, v165
	v_mov_b32_e32 v70, v166
	v_mov_b32_e32 v71, v167
	v_mov_b32_e32 v72, v168
	v_mov_b32_e32 v73, v169
	v_mov_b32_e32 v74, v170
	v_mov_b32_e32 v75, v171
	v_mov_b32_e32 v240, v164
	v_mov_b32_e32 v241, v165
	v_mov_b32_e32 v242, v166
	v_mov_b32_e32 v243, v167
	v_mov_b32_e32 v244, v168
	v_mov_b32_e32 v245, v169
	v_mov_b32_e32 v246, v170
	v_mov_b32_e32 v247, v171
	v_fmamk_f32 v78, v78, 0x3a800000, v214
	v_mul_f32_e32 v79, 0x4b800000, v78
	v_cmp_gt_f32_e32 vcc, s9, v78
	s_nop 1
	v_cndmask_b32_e32 v78, v78, v79, vcc
	v_rsq_f32_e32 v78, v78
	s_nop 0
	v_mul_f32_e32 v79, 0x45800000, v78
	v_cndmask_b32_e32 v78, v78, v79, vcc
	v_pk_fma_f32 v[70:71], v[66:67], v[78:79], v[70:71] op_sel_hi:[1,0,1]
	v_pk_fma_f32 v[68:69], v[64:65], v[78:79], v[68:69] op_sel_hi:[1,0,1]
	v_pk_fma_f32 v[74:75], v[62:63], v[78:79], v[74:75] op_sel_hi:[1,0,1]
	v_pk_fma_f32 v[72:73], v[60:61], v[78:79], v[72:73] op_sel_hi:[1,0,1]
